# v50-lds-dma-staging
# speedup vs baseline: 1.0067x; 1.0067x over previous
.LBB0_655:
	s_waitcnt vmcnt(0)
	v_mbcnt_lo_u32_b32 v236, -1, 0
	v_mbcnt_hi_u32_b32 v236, -1, v236
	s_add_i32 s98, s90, 0
	s_movk_i32 s100, 3856
	s_cmp_ge_u32 s98, 34
	s_cselect_b32 s100, 3277, s100
	s_cselect_b32 s101, 20, 17
	s_cselect_b32 s99, 34, 0
	s_sub_u32 s98, s98, s99
	s_lshl_b32 s98, s98, 6
	s_cmp_eq_u32 s101, 20
	s_cselect_b32 s99, 2048, 0
	v_add_u32_e32 v230, s98, v236
	v_mul_u32_u24_e32 v231, s100, v230
	v_lshrrev_b32_e32 v231, 16, v231
	v_mul_u32_u24_e32 v232, s101, v231
	v_sub_u32_e32 v232, v230, v232
	v_min_u32_e32 v232, 15, v232
	v_mul_u32_u24_e32 v233, 0x3000, v231
	v_lshl_add_u32 v238, v232, 4, v233
	v_add_u32_e32 v238, s99, v238
	s_add_i32 s98, s90, 8
	s_movk_i32 s100, 3856
	s_cmp_ge_u32 s98, 34
	s_cselect_b32 s100, 3277, s100
	s_cselect_b32 s101, 20, 17
	s_cselect_b32 s99, 34, 0
	s_sub_u32 s98, s98, s99
	s_lshl_b32 s98, s98, 6
	s_cmp_eq_u32 s101, 20
	s_cselect_b32 s99, 2048, 0
	v_add_u32_e32 v230, s98, v236
	v_mul_u32_u24_e32 v231, s100, v230
	v_lshrrev_b32_e32 v231, 16, v231
	v_mul_u32_u24_e32 v232, s101, v231
	v_sub_u32_e32 v232, v230, v232
	v_min_u32_e32 v232, 15, v232
	v_mul_u32_u24_e32 v233, 0x3000, v231
	v_lshl_add_u32 v239, v232, 4, v233
	v_add_u32_e32 v239, s99, v239
	s_add_i32 s98, s90, 16
	s_movk_i32 s100, 3856
	s_cmp_ge_u32 s98, 34
	s_cselect_b32 s100, 3277, s100
	s_cselect_b32 s101, 20, 17
	s_cselect_b32 s99, 34, 0
	s_sub_u32 s98, s98, s99
	s_lshl_b32 s98, s98, 6
	s_cmp_eq_u32 s101, 20
	s_cselect_b32 s99, 2048, 0
	v_add_u32_e32 v230, s98, v236
	v_mul_u32_u24_e32 v231, s100, v230
	v_lshrrev_b32_e32 v231, 16, v231
	v_mul_u32_u24_e32 v232, s101, v231
	v_sub_u32_e32 v232, v230, v232
	v_min_u32_e32 v232, 15, v232
	v_mul_u32_u24_e32 v233, 0x3000, v231
	v_lshl_add_u32 v240, v232, 4, v233
	v_add_u32_e32 v240, s99, v240
	s_add_i32 s98, s90, 24
	s_movk_i32 s100, 3856
	s_cmp_ge_u32 s98, 34
	s_cselect_b32 s100, 3277, s100
	s_cselect_b32 s101, 20, 17
	s_cselect_b32 s99, 34, 0
	s_sub_u32 s98, s98, s99
	s_lshl_b32 s98, s98, 6
	s_cmp_eq_u32 s101, 20
	s_cselect_b32 s99, 2048, 0
	v_add_u32_e32 v230, s98, v236
	v_mul_u32_u24_e32 v231, s100, v230
	v_lshrrev_b32_e32 v231, 16, v231
	v_mul_u32_u24_e32 v232, s101, v231
	v_sub_u32_e32 v232, v230, v232
	v_min_u32_e32 v232, 15, v232
	v_mul_u32_u24_e32 v233, 0x3000, v231
	v_lshl_add_u32 v241, v232, 4, v233
	v_add_u32_e32 v241, s99, v241
	s_add_i32 s98, s90, 32
	s_movk_i32 s100, 3856
	s_cmp_ge_u32 s98, 34
	s_cselect_b32 s100, 3277, s100
	s_cselect_b32 s101, 20, 17
	s_cselect_b32 s99, 34, 0
	s_sub_u32 s98, s98, s99
	s_lshl_b32 s98, s98, 6
	s_cmp_eq_u32 s101, 20
	s_cselect_b32 s99, 2048, 0
	v_add_u32_e32 v230, s98, v236
	v_mul_u32_u24_e32 v231, s100, v230
	v_lshrrev_b32_e32 v231, 16, v231
	v_mul_u32_u24_e32 v232, s101, v231
	v_sub_u32_e32 v232, v230, v232
	v_min_u32_e32 v232, 15, v232
	v_mul_u32_u24_e32 v233, 0x3000, v231
	v_lshl_add_u32 v242, v232, 4, v233
	v_add_u32_e32 v242, s99, v242
	s_add_i32 s98, s90, 40
	s_movk_i32 s100, 3856
	s_cmp_ge_u32 s98, 34
	s_cselect_b32 s100, 3277, s100
	s_cselect_b32 s101, 20, 17
	s_cselect_b32 s99, 34, 0
	s_sub_u32 s98, s98, s99
	s_lshl_b32 s98, s98, 6
	s_cmp_eq_u32 s101, 20
	s_cselect_b32 s99, 2048, 0
	v_add_u32_e32 v230, s98, v236
	v_mul_u32_u24_e32 v231, s100, v230
	v_lshrrev_b32_e32 v231, 16, v231
	v_mul_u32_u24_e32 v232, s101, v231
	v_sub_u32_e32 v232, v230, v232
	v_min_u32_e32 v232, 15, v232
	v_mul_u32_u24_e32 v233, 0x3000, v231
	v_lshl_add_u32 v243, v232, 4, v233
	v_add_u32_e32 v243, s99, v243
	s_add_i32 s98, s90, 48
	s_movk_i32 s100, 3856
	s_cmp_ge_u32 s98, 34
	s_cselect_b32 s100, 3277, s100
	s_cselect_b32 s101, 20, 17
	s_cselect_b32 s99, 34, 0
	s_sub_u32 s98, s98, s99
	s_lshl_b32 s98, s98, 6
	s_cmp_eq_u32 s101, 20
	s_cselect_b32 s99, 2048, 0
	v_add_u32_e32 v230, s98, v236
	v_mul_u32_u24_e32 v231, s100, v230
	v_lshrrev_b32_e32 v231, 16, v231
	v_mul_u32_u24_e32 v232, s101, v231
	v_sub_u32_e32 v232, v230, v232
	v_min_u32_e32 v232, 15, v232
	v_mul_u32_u24_e32 v233, 0x3000, v231
	v_lshl_add_u32 v244, v232, 4, v233
	v_add_u32_e32 v244, s99, v244
	s_add_i32 s98, s90, 56
	s_movk_i32 s100, 3856
	s_cmp_ge_u32 s98, 34
	s_cselect_b32 s100, 3277, s100
	s_cselect_b32 s101, 20, 17
	s_cselect_b32 s99, 34, 0
	s_sub_u32 s98, s98, s99
	s_lshl_b32 s98, s98, 6
	s_cmp_eq_u32 s101, 20
	s_cselect_b32 s99, 2048, 0
	v_add_u32_e32 v230, s98, v236
	v_mul_u32_u24_e32 v231, s100, v230
	v_lshrrev_b32_e32 v231, 16, v231
	v_mul_u32_u24_e32 v232, s101, v231
	v_sub_u32_e32 v232, v230, v232
	v_min_u32_e32 v232, 15, v232
	v_mul_u32_u24_e32 v233, 0x3000, v231
	v_lshl_add_u32 v245, v232, 4, v233
	v_add_u32_e32 v245, s99, v245
	s_add_i32 s98, s90, 64
	s_movk_i32 s100, 3856
	s_cmp_ge_u32 s98, 34
	s_cselect_b32 s100, 3277, s100
	s_cselect_b32 s101, 20, 17
	s_cselect_b32 s99, 34, 0
	s_sub_u32 s98, s98, s99
	s_lshl_b32 s98, s98, 6
	s_cmp_eq_u32 s101, 20
	s_cselect_b32 s99, 2048, 0
	v_add_u32_e32 v230, s98, v236
	v_mul_u32_u24_e32 v231, s100, v230
	v_lshrrev_b32_e32 v231, 16, v231
	v_mul_u32_u24_e32 v232, s101, v231
	v_sub_u32_e32 v232, v230, v232
	v_min_u32_e32 v232, 15, v232
	v_mul_u32_u24_e32 v233, 0x3000, v231
	v_lshl_add_u32 v246, v232, 4, v233
	v_add_u32_e32 v246, s99, v246
	s_cmp_lt_u32 s90, 2
	s_cselect_b32 s98, 72, 64
	s_add_i32 s98, s90, s98
	s_movk_i32 s100, 3856
	s_cmp_ge_u32 s98, 34
	s_cselect_b32 s100, 3277, s100
	s_cselect_b32 s101, 20, 17
	s_cselect_b32 s99, 34, 0
	s_sub_u32 s98, s98, s99
	s_lshl_b32 s98, s98, 6
	s_cmp_eq_u32 s101, 20
	s_cselect_b32 s99, 2048, 0
	v_add_u32_e32 v230, s98, v236
	v_mul_u32_u24_e32 v231, s100, v230
	v_lshrrev_b32_e32 v231, 16, v231
	v_mul_u32_u24_e32 v232, s101, v231
	v_sub_u32_e32 v232, v230, v232
	v_min_u32_e32 v232, 15, v232
	v_mul_u32_u24_e32 v233, 0x3000, v231
	v_lshl_add_u32 v247, v232, 4, v233
	v_add_u32_e32 v247, s99, v247
	v_mov_b32_e32 v235, 0
	s_bitcmp1_b32 s72, 0
	s_cselect_b32 s46, 0x12800, 0
	s_xor_b32 s12, s46, 0x12800
	v_add_u32_e32 v230, s46, v181
	ds_read_b128 v[194:197], v230 offset:0
	ds_read_b128 v[198:201], v230 offset:32
	ds_read_b128 v[202:205], v230 offset:64
	ds_read_b128 v[206:209], v230 offset:96
	ds_read_b128 v[210:213], v230 offset:8704
	ds_read_b128 v[214:217], v230 offset:8736
	ds_read_b128 v[218:221], v230 offset:8768
	ds_read_b128 v[226:229], v230 offset:8800
	v_add_u32_e32 v231, s46, v185
	v_add_u32_e32 v232, 0x8800, v231
	v_add_u32_e32 v233, s12, v186
	v_add_u32_e32 v234, s12, v1
	s_branch .Ldf_qk

.Ldf_qk:
	s_waitcnt lgkmcnt(7)
	v_mfma_f32_32x32x16_bf16 v[82:97], v[194:197], v[158:161], v[2:17]
	s_waitcnt lgkmcnt(6)
	ds_read_b128 v[194:197], v230 offset:17408
	s_add_u32 s98, s44, s58
	s_addc_u32 s99, s45, 0
	s_add_u32 s98, s98, s74
	s_addc_u32 s99, s99, s75
	s_add_u32 s98, s98, s26
	s_addc_u32 s99, s99, s27
	s_lshl_b32 s100, s90, 10
	s_add_i32 s100, s100, s12
	s_add_i32 m0, s100, 0x0
	s_nop 0
	global_load_lds_dwordx4 v238, s[98:99]
	v_mfma_f32_32x32x16_bf16 v[82:97], v[198:201], v[154:157], v[82:97]
	s_waitcnt lgkmcnt(6)
	ds_read_b128 v[198:201], v230 offset:17440
	v_mfma_f32_32x32x16_bf16 v[82:97], v[202:205], v[150:153], v[82:97]
	s_waitcnt lgkmcnt(6)
	ds_read_b128 v[202:205], v230 offset:17472
	s_add_i32 m0, s100, 0x2000
	s_nop 0
	global_load_lds_dwordx4 v239, s[98:99]
	v_mfma_f32_32x32x16_bf16 v[82:97], v[206:209], v[146:149], v[82:97]
	s_waitcnt lgkmcnt(6)
	ds_read_b128 v[206:209], v230 offset:17504
	v_mfma_f32_32x32x16_bf16 v[98:113], v[210:213], v[158:161], v[2:17]
	s_waitcnt lgkmcnt(6)
	ds_read_b128 v[210:213], v230 offset:26112
	s_add_i32 m0, s100, 0x4000
	s_nop 0
	global_load_lds_dwordx4 v240, s[98:99]
	v_mfma_f32_32x32x16_bf16 v[98:113], v[214:217], v[154:157], v[98:113]
	s_waitcnt lgkmcnt(6)
	ds_read_b128 v[214:217], v230 offset:26144
	v_mfma_f32_32x32x16_bf16 v[98:113], v[218:221], v[150:153], v[98:113]
	s_waitcnt lgkmcnt(6)
	ds_read_b128 v[218:221], v230 offset:26176
	s_add_i32 m0, s100, 0x6000
	s_nop 0
	global_load_lds_dwordx4 v241, s[98:99]
	v_mfma_f32_32x32x16_bf16 v[98:113], v[226:229], v[146:149], v[98:113]
	s_waitcnt lgkmcnt(6)
	ds_read_b128 v[226:229], v230 offset:26208
	v_mfma_f32_32x32x16_bf16 v[114:129], v[194:197], v[158:161], v[2:17]
	s_waitcnt lgkmcnt(6)
	ds_read_b64_tr_b16 v[194:195], v231 offset:34816
	ds_read_b64_tr_b16 v[196:197], v231 offset:37376
	v_exp_f32_e32 v82, v82
	v_exp_f32_e32 v83, v83
	s_add_i32 m0, s100, 0x8000
	s_nop 0
	global_load_lds_dwordx4 v242, s[98:99]
	v_add_f32_e32 v191, v191, v82
	v_add_f32_e32 v235, v235, v83
	v_cvt_pk_bf16_f32 v82, v82, v83
	v_mfma_f32_32x32x16_bf16 v[114:129], v[198:201], v[154:157], v[114:129]
	s_waitcnt lgkmcnt(7)
	ds_read_b64_tr_b16 v[198:199], v231 offset:34880
	ds_read_b64_tr_b16 v[200:201], v231 offset:37440
	v_exp_f32_e32 v84, v84
	v_exp_f32_e32 v85, v85
	v_add_f32_e32 v191, v191, v84
	v_add_f32_e32 v235, v235, v85
	v_cvt_pk_bf16_f32 v83, v84, v85
	v_mfma_f32_32x32x16_bf16 v[114:129], v[202:205], v[150:153], v[114:129]
	s_waitcnt lgkmcnt(8)
	ds_read_b64_tr_b16 v[202:203], v231 offset:34944
	ds_read_b64_tr_b16 v[204:205], v231 offset:37504
	v_exp_f32_e32 v86, v86
	v_exp_f32_e32 v87, v87
	s_add_i32 m0, s100, 0xa000
	s_nop 0
	global_load_lds_dwordx4 v243, s[98:99]
	v_add_f32_e32 v191, v191, v86
	v_add_f32_e32 v235, v235, v87
	v_cvt_pk_bf16_f32 v84, v86, v87
	v_mfma_f32_32x32x16_bf16 v[114:129], v[206:209], v[146:149], v[114:129]
	s_waitcnt lgkmcnt(9)
	ds_read_b64_tr_b16 v[206:207], v231 offset:35008
	ds_read_b64_tr_b16 v[208:209], v231 offset:37568
	v_exp_f32_e32 v88, v88
	v_exp_f32_e32 v89, v89
	v_add_f32_e32 v191, v191, v88
	v_add_f32_e32 v235, v235, v89
	v_cvt_pk_bf16_f32 v85, v88, v89
	v_mfma_f32_32x32x16_bf16 v[130:145], v[210:213], v[158:161], v[2:17]
	s_waitcnt lgkmcnt(10)
	ds_read_b64_tr_b16 v[210:211], v231 offset:39936
	ds_read_b64_tr_b16 v[212:213], v231 offset:42496
	v_exp_f32_e32 v90, v90
	v_exp_f32_e32 v91, v91
	s_add_i32 m0, s100, 0xc000
	s_nop 0
	global_load_lds_dwordx4 v244, s[98:99]
	v_add_f32_e32 v191, v191, v90
	v_add_f32_e32 v235, v235, v91
	v_cvt_pk_bf16_f32 v86, v90, v91
	v_mfma_f32_32x32x16_bf16 v[130:145], v[214:217], v[154:157], v[130:145]
	s_waitcnt lgkmcnt(11)
	ds_read_b64_tr_b16 v[214:215], v231 offset:40000
	ds_read_b64_tr_b16 v[216:217], v231 offset:42560
	v_exp_f32_e32 v92, v92
	v_exp_f32_e32 v93, v93
	v_add_f32_e32 v191, v191, v92
	v_add_f32_e32 v235, v235, v93
	v_cvt_pk_bf16_f32 v87, v92, v93
	v_mfma_f32_32x32x16_bf16 v[130:145], v[218:221], v[150:153], v[130:145]
	s_waitcnt lgkmcnt(12)
	ds_read_b64_tr_b16 v[218:219], v231 offset:40064
	ds_read_b64_tr_b16 v[220:221], v231 offset:42624
	v_exp_f32_e32 v94, v94
	v_exp_f32_e32 v95, v95
	s_add_i32 m0, s100, 0xe000
	s_nop 0
	global_load_lds_dwordx4 v245, s[98:99]
	v_add_f32_e32 v191, v191, v94
	v_add_f32_e32 v235, v235, v95
	v_cvt_pk_bf16_f32 v88, v94, v95
	v_mfma_f32_32x32x16_bf16 v[130:145], v[226:229], v[146:149], v[130:145]
	s_waitcnt lgkmcnt(12)
	ds_read_b64_tr_b16 v[226:227], v231 offset:40128
	ds_read_b64_tr_b16 v[228:229], v231 offset:42688
	v_exp_f32_e32 v96, v96
	v_exp_f32_e32 v97, v97
	v_add_f32_e32 v191, v191, v96
	v_add_f32_e32 v235, v235, v97
	v_cvt_pk_bf16_f32 v89, v96, v97
	v_mfma_f32_32x32x16_bf16 v[50:65], v[194:197], v[82:85], v[50:65]
	s_waitcnt lgkmcnt(12)
	ds_read_b64_tr_b16 v[194:195], v231 offset:45056
	ds_read_b64_tr_b16 v[196:197], v231 offset:47616
	v_exp_f32_e32 v98, v98
	v_exp_f32_e32 v99, v99
	s_add_i32 m0, s100, 0x10000
	s_nop 0
	global_load_lds_dwordx4 v246, s[98:99]
	v_add_f32_e32 v191, v191, v98
	v_add_f32_e32 v235, v235, v99
	v_cvt_pk_bf16_f32 v98, v98, v99
	v_mfma_f32_32x32x16_bf16 v[66:81], v[198:201], v[82:85], v[66:81]
	s_waitcnt lgkmcnt(12)
	ds_read_b64_tr_b16 v[198:199], v231 offset:45120
	ds_read_b64_tr_b16 v[200:201], v231 offset:47680
	v_exp_f32_e32 v100, v100
	v_exp_f32_e32 v101, v101
	v_add_f32_e32 v191, v191, v100
	v_add_f32_e32 v235, v235, v101
	v_cvt_pk_bf16_f32 v99, v100, v101
	v_mfma_f32_32x32x16_bf16 v[34:49], v[202:205], v[82:85], v[34:49]
	s_waitcnt lgkmcnt(12)
	ds_read_b64_tr_b16 v[202:203], v231 offset:45184
	ds_read_b64_tr_b16 v[204:205], v231 offset:47744
	v_exp_f32_e32 v102, v102
	v_exp_f32_e32 v103, v103
	s_mov_b32 s101, 0x10000
	s_cmp_lt_u32 s90, 2
	s_cselect_b32 s101, 0x12000, s101
	s_add_i32 m0, s100, s101
	s_nop 0
	global_load_lds_dwordx4 v247, s[98:99]
	v_add_f32_e32 v191, v191, v102
	v_add_f32_e32 v235, v235, v103
	v_cvt_pk_bf16_f32 v100, v102, v103
	v_mfma_f32_32x32x16_bf16 v[18:33], v[206:209], v[82:85], v[18:33]
	s_waitcnt lgkmcnt(12)
	ds_read_b64_tr_b16 v[206:207], v231 offset:45248
	ds_read_b64_tr_b16 v[208:209], v231 offset:47808
	v_exp_f32_e32 v104, v104
	v_exp_f32_e32 v105, v105
	v_add_f32_e32 v191, v191, v104
	v_add_f32_e32 v235, v235, v105
	v_cvt_pk_bf16_f32 v101, v104, v105
	v_mfma_f32_32x32x16_bf16 v[50:65], v[210:213], v[86:89], v[50:65]
	s_waitcnt lgkmcnt(12)
	ds_read_b64_tr_b16 v[210:211], v231 offset:50176
	ds_read_b64_tr_b16 v[212:213], v231 offset:52736
	v_exp_f32_e32 v106, v106
	v_exp_f32_e32 v107, v107
	v_add_f32_e32 v191, v191, v106
	v_add_f32_e32 v235, v235, v107
	v_cvt_pk_bf16_f32 v102, v106, v107
	v_mfma_f32_32x32x16_bf16 v[66:81], v[214:217], v[86:89], v[66:81]
	s_waitcnt lgkmcnt(12)
	ds_read_b64_tr_b16 v[214:215], v231 offset:50240
	ds_read_b64_tr_b16 v[216:217], v231 offset:52800
	v_exp_f32_e32 v108, v108
	v_exp_f32_e32 v109, v109
	v_add_f32_e32 v191, v191, v108
	v_add_f32_e32 v235, v235, v109
	v_cvt_pk_bf16_f32 v103, v108, v109
	v_mfma_f32_32x32x16_bf16 v[34:49], v[218:221], v[86:89], v[34:49]
	s_waitcnt lgkmcnt(12)
	ds_read_b64_tr_b16 v[218:219], v231 offset:50304
	ds_read_b64_tr_b16 v[220:221], v231 offset:52864
	v_exp_f32_e32 v110, v110
	v_exp_f32_e32 v111, v111
	v_add_f32_e32 v191, v191, v110
	v_add_f32_e32 v235, v235, v111
	v_cvt_pk_bf16_f32 v104, v110, v111
	v_mfma_f32_32x32x16_bf16 v[18:33], v[226:229], v[86:89], v[18:33]
	s_waitcnt lgkmcnt(12)
	ds_read_b64_tr_b16 v[226:227], v231 offset:50368
	ds_read_b64_tr_b16 v[228:229], v231 offset:52928
	v_exp_f32_e32 v112, v112
	v_exp_f32_e32 v113, v113
	v_add_f32_e32 v191, v191, v112
	v_add_f32_e32 v235, v235, v113
	v_cvt_pk_bf16_f32 v105, v112, v113
	v_mfma_f32_32x32x16_bf16 v[50:65], v[194:197], v[98:101], v[50:65]
	s_waitcnt lgkmcnt(12)
	ds_read_b64_tr_b16 v[194:195], v232 offset:20480
	ds_read_b64_tr_b16 v[196:197], v232 offset:23040
	v_exp_f32_e32 v114, v114
	v_exp_f32_e32 v115, v115
	v_add_f32_e32 v191, v191, v114
	v_add_f32_e32 v235, v235, v115
	v_cvt_pk_bf16_f32 v114, v114, v115
	v_mfma_f32_32x32x16_bf16 v[66:81], v[198:201], v[98:101], v[66:81]
	s_waitcnt lgkmcnt(12)
	ds_read_b64_tr_b16 v[198:199], v232 offset:20544
	ds_read_b64_tr_b16 v[200:201], v232 offset:23104
	v_exp_f32_e32 v116, v116
	v_exp_f32_e32 v117, v117
	v_add_f32_e32 v191, v191, v116
	v_add_f32_e32 v235, v235, v117
	v_cvt_pk_bf16_f32 v115, v116, v117
	v_mfma_f32_32x32x16_bf16 v[34:49], v[202:205], v[98:101], v[34:49]
	s_waitcnt lgkmcnt(12)
	ds_read_b64_tr_b16 v[202:203], v232 offset:20608
	ds_read_b64_tr_b16 v[204:205], v232 offset:23168
	v_exp_f32_e32 v118, v118
	v_exp_f32_e32 v119, v119
	v_add_f32_e32 v191, v191, v118
	v_add_f32_e32 v235, v235, v119
	v_cvt_pk_bf16_f32 v116, v118, v119
	v_mfma_f32_32x32x16_bf16 v[18:33], v[206:209], v[98:101], v[18:33]
	s_waitcnt lgkmcnt(12)
	ds_read_b64_tr_b16 v[206:207], v232 offset:20672
	ds_read_b64_tr_b16 v[208:209], v232 offset:23232
	v_exp_f32_e32 v120, v120
	v_exp_f32_e32 v121, v121
	v_add_f32_e32 v191, v191, v120
	v_add_f32_e32 v235, v235, v121
	v_cvt_pk_bf16_f32 v117, v120, v121
	v_mfma_f32_32x32x16_bf16 v[50:65], v[210:213], v[102:105], v[50:65]
	s_waitcnt lgkmcnt(12)
	ds_read_b64_tr_b16 v[210:211], v232 offset:25600
	ds_read_b64_tr_b16 v[212:213], v232 offset:28160
	v_exp_f32_e32 v122, v122
	v_exp_f32_e32 v123, v123
	v_add_f32_e32 v191, v191, v122
	v_add_f32_e32 v235, v235, v123
	v_cvt_pk_bf16_f32 v118, v122, v123
	v_mfma_f32_32x32x16_bf16 v[66:81], v[214:217], v[102:105], v[66:81]
	s_waitcnt lgkmcnt(12)
	ds_read_b64_tr_b16 v[214:215], v232 offset:25664
	ds_read_b64_tr_b16 v[216:217], v232 offset:28224
	v_exp_f32_e32 v124, v124
	v_exp_f32_e32 v125, v125
	v_add_f32_e32 v191, v191, v124
	v_add_f32_e32 v235, v235, v125
	v_cvt_pk_bf16_f32 v119, v124, v125
	v_mfma_f32_32x32x16_bf16 v[34:49], v[218:221], v[102:105], v[34:49]
	s_waitcnt lgkmcnt(12)
	ds_read_b64_tr_b16 v[218:219], v232 offset:25728
	ds_read_b64_tr_b16 v[220:221], v232 offset:28288
	v_exp_f32_e32 v126, v126
	v_exp_f32_e32 v127, v127
	v_add_f32_e32 v191, v191, v126
	v_add_f32_e32 v235, v235, v127
	v_cvt_pk_bf16_f32 v120, v126, v127
	v_mfma_f32_32x32x16_bf16 v[18:33], v[226:229], v[102:105], v[18:33]
	s_waitcnt lgkmcnt(12)
	ds_read_b64_tr_b16 v[226:227], v232 offset:25792
	ds_read_b64_tr_b16 v[228:229], v232 offset:28352
	v_exp_f32_e32 v128, v128
	v_exp_f32_e32 v129, v129
	v_add_f32_e32 v191, v191, v128
	v_add_f32_e32 v235, v235, v129
	v_cvt_pk_bf16_f32 v121, v128, v129
	v_mfma_f32_32x32x16_bf16 v[50:65], v[194:197], v[114:117], v[50:65]
	s_waitcnt lgkmcnt(12)
	ds_read_b64_tr_b16 v[194:195], v232 offset:30720
	ds_read_b64_tr_b16 v[196:197], v232 offset:33280
	v_exp_f32_e32 v130, v130
	v_exp_f32_e32 v131, v131
	v_add_f32_e32 v191, v191, v130
	v_add_f32_e32 v235, v235, v131
	v_cvt_pk_bf16_f32 v130, v130, v131
	v_mfma_f32_32x32x16_bf16 v[66:81], v[198:201], v[114:117], v[66:81]
	s_waitcnt lgkmcnt(12)
	ds_read_b64_tr_b16 v[198:199], v232 offset:30784
	ds_read_b64_tr_b16 v[200:201], v232 offset:33344
	v_exp_f32_e32 v132, v132
	v_exp_f32_e32 v133, v133
	v_add_f32_e32 v191, v191, v132
	v_add_f32_e32 v235, v235, v133
	v_cvt_pk_bf16_f32 v131, v132, v133
	v_mfma_f32_32x32x16_bf16 v[34:49], v[202:205], v[114:117], v[34:49]
	s_waitcnt lgkmcnt(12)
	ds_read_b64_tr_b16 v[202:203], v232 offset:30848
	ds_read_b64_tr_b16 v[204:205], v232 offset:33408
	v_exp_f32_e32 v134, v134
	v_exp_f32_e32 v135, v135
	v_add_f32_e32 v191, v191, v134
	v_add_f32_e32 v235, v235, v135
	v_cvt_pk_bf16_f32 v132, v134, v135
	v_mfma_f32_32x32x16_bf16 v[18:33], v[206:209], v[114:117], v[18:33]
	s_waitcnt lgkmcnt(12)
	ds_read_b64_tr_b16 v[206:207], v232 offset:30912
	ds_read_b64_tr_b16 v[208:209], v232 offset:33472
	v_exp_f32_e32 v136, v136
	v_exp_f32_e32 v137, v137
	v_add_f32_e32 v191, v191, v136
	v_add_f32_e32 v235, v235, v137
	v_cvt_pk_bf16_f32 v133, v136, v137
	v_mfma_f32_32x32x16_bf16 v[50:65], v[210:213], v[118:121], v[50:65]
	s_waitcnt lgkmcnt(12)
	ds_read_b64_tr_b16 v[210:211], v232 offset:35840
	ds_read_b64_tr_b16 v[212:213], v232 offset:38400
	v_exp_f32_e32 v138, v138
	v_exp_f32_e32 v139, v139
	v_add_f32_e32 v191, v191, v138
	v_add_f32_e32 v235, v235, v139
	v_cvt_pk_bf16_f32 v134, v138, v139
	v_mfma_f32_32x32x16_bf16 v[66:81], v[214:217], v[118:121], v[66:81]
	s_waitcnt lgkmcnt(12)
	ds_read_b64_tr_b16 v[214:215], v232 offset:35904
	ds_read_b64_tr_b16 v[216:217], v232 offset:38464
	v_exp_f32_e32 v140, v140
	v_exp_f32_e32 v141, v141
	v_add_f32_e32 v191, v191, v140
	v_add_f32_e32 v235, v235, v141
	v_cvt_pk_bf16_f32 v135, v140, v141
	v_mfma_f32_32x32x16_bf16 v[34:49], v[218:221], v[118:121], v[34:49]
	s_waitcnt lgkmcnt(12)
	ds_read_b64_tr_b16 v[218:219], v232 offset:35968
	ds_read_b64_tr_b16 v[220:221], v232 offset:38528
	v_exp_f32_e32 v142, v142
	v_exp_f32_e32 v143, v143
	v_add_f32_e32 v191, v191, v142
	v_add_f32_e32 v235, v235, v143
	v_cvt_pk_bf16_f32 v136, v142, v143
	v_mfma_f32_32x32x16_bf16 v[18:33], v[226:229], v[118:121], v[18:33]
	s_waitcnt lgkmcnt(12)
	ds_read_b64_tr_b16 v[226:227], v232 offset:36032
	ds_read_b64_tr_b16 v[228:229], v232 offset:38592
	v_exp_f32_e32 v144, v144
	v_exp_f32_e32 v145, v145
	v_add_f32_e32 v191, v191, v144
	v_add_f32_e32 v235, v235, v145
	v_cvt_pk_bf16_f32 v137, v144, v145
	v_mfma_f32_32x32x16_bf16 v[50:65], v[194:197], v[130:133], v[50:65]
	s_waitcnt lgkmcnt(12)
	v_mfma_f32_32x32x16_bf16 v[66:81], v[198:201], v[130:133], v[66:81]
	s_waitcnt lgkmcnt(10)
	v_mfma_f32_32x32x16_bf16 v[34:49], v[202:205], v[130:133], v[34:49]
	s_waitcnt lgkmcnt(8)
	v_mfma_f32_32x32x16_bf16 v[18:33], v[206:209], v[130:133], v[18:33]
	s_waitcnt vmcnt(0)
	s_add_i32 s72, s72, 1
	s_add_u32 s44, s44, 0x180000
	s_addc_u32 s45, s45, 0
	s_cmp_eq_u32 s44, 0x2e80000
	s_waitcnt lgkmcnt(0)
	s_barrier
	s_cbranch_scc0 .Ldf_loop
	v_mfma_f32_32x32x16_bf16 v[50:65], v[210:213], v[134:137], v[50:65]
	v_mfma_f32_32x32x16_bf16 v[66:81], v[214:217], v[134:137], v[66:81]
	v_mfma_f32_32x32x16_bf16 v[34:49], v[218:221], v[134:137], v[34:49]
	v_mfma_f32_32x32x16_bf16 v[18:33], v[226:229], v[134:137], v[18:33]
	v_add_u32_e32 v238, 0x21480, v185
	v_add_u32_e32 v239, 0x21e80, v185
	v_add_u32_e32 v240, 0x214c0, v185
	v_add_u32_e32 v241, 0x21ec0, v185
	v_add_u32_e32 v242, 0x22800, v185
	v_add_u32_e32 v243, 0x23200, v185
	v_add_u32_e32 v244, 0x22840, v185
	v_add_u32_e32 v245, 0x23240, v185
	v_add_u32_e32 v246, 0x22880, v185
	v_add_u32_e32 v247, 0x23280, v185
	v_add_u32_e32 v248, 0x228c0, v185
	v_add_u32_e32 v249, 0x232c0, v185
	v_add_u32_e32 v250, 0x23c00, v185
	v_add_u32_e32 v251, 0x24600, v185
	v_add_u32_e32 v252, 0x23c40, v185
	v_add_u32_e32 v253, 0x24640, v185
	v_add_f32_e32 v191, v191, v235
	v_add_u32_e32 v82, 0x12800, v181
	ds_read_b128 v[82:85], v82
	v_add_u32_e32 v90, 0x12820, v181
	v_add_u32_e32 v94, 0x12840, v181
	v_add_u32_e32 v86, 0x14a00, v181
	ds_read_b128 v[86:89], v86
	v_add_u32_e32 v98, 0x12860, v181
	s_waitcnt lgkmcnt(1)
	v_mfma_f32_32x32x16_bf16 v[114:129], v[82:85], v[158:161], v[2:17]
	ds_read_b128 v[82:85], v90
	v_add_u32_e32 v90, 0x14a20, v181
	ds_read_b128 v[90:93], v90
	s_waitcnt lgkmcnt(1)
	v_mfma_f32_32x32x16_bf16 v[114:129], v[82:85], v[154:157], v[114:129]
	ds_read_b128 v[82:85], v94
	v_add_u32_e32 v94, 0x14a40, v181
	ds_read_b128 v[94:97], v94
	s_waitcnt lgkmcnt(1)
	v_mfma_f32_32x32x16_bf16 v[114:129], v[82:85], v[150:153], v[114:129]
	ds_read_b128 v[82:85], v98
	v_add_u32_e32 v98, 0x14a60, v181
	ds_read_b128 v[130:133], v98
	v_mfma_f32_32x32x16_bf16 v[98:113], v[86:89], v[158:161], v[2:17]
	v_add_u32_e32 v86, 0x18e00, v181
	ds_read_b128 v[168:171], v86
	v_mfma_f32_32x32x16_bf16 v[98:113], v[90:93], v[154:157], v[98:113]
	s_waitcnt lgkmcnt(3)
	v_mfma_f32_32x32x16_bf16 v[98:113], v[94:97], v[150:153], v[98:113]
	s_waitcnt lgkmcnt(2)
	v_mfma_f32_32x32x16_bf16 v[114:129], v[82:85], v[146:149], v[114:129]
	v_add_u32_e32 v82, 0x16c00, v181
	ds_read_b128 v[82:85], v82
	s_waitcnt lgkmcnt(2)
	v_mfma_f32_32x32x16_bf16 v[98:113], v[130:133], v[146:149], v[98:113]
	s_nop 7
	v_exp_f32_e32 v163, v114
	v_exp_f32_e32 v165, v116
	v_exp_f32_e32 v162, v117
	v_exp_f32_e32 v116, v119
	v_exp_f32_e32 v117, v120
	v_exp_f32_e32 v114, v122
	v_exp_f32_e32 v122, v124
	s_waitcnt lgkmcnt(0)
	v_mfma_f32_32x32x16_bf16 v[130:145], v[82:85], v[158:161], v[2:17]
	v_add_u32_e32 v82, 0x16c20, v181
	ds_read_b128 v[172:175], v82
	v_exp_f32_e32 v166, v98
	v_exp_f32_e32 v98, v121
	v_exp_f32_e32 v119, v126
	v_exp_f32_e32 v120, v127
	v_exp_f32_e32 v121, v128
	v_mfma_f32_32x32x16_bf16 v[82:97], v[168:171], v[158:161], v[2:17]
	v_exp_f32_e32 v168, v99
	v_add_u32_e32 v99, 0x18e20, v181
	ds_read_b128 v[192:195], v99
	v_add_u32_e32 v99, 0x16c40, v181
	v_exp_f32_e32 v124, v129
	ds_read_b128 v[126:129], v99
	v_add_u32_e32 v99, 0x18e40, v181
	s_waitcnt lgkmcnt(2)
	v_mfma_f32_32x32x16_bf16 v[130:145], v[172:175], v[154:157], v[130:145]
	ds_read_b128 v[174:177], v99
	v_add_u32_e32 v99, 0x16c60, v181
	v_exp_f32_e32 v169, v100
	v_exp_f32_e32 v173, v101
	v_exp_f32_e32 v160, v102
	v_exp_f32_e32 v159, v103
	ds_read_b128 v[100:103], v99
	s_waitcnt lgkmcnt(3)
	v_mfma_f32_32x32x16_bf16 v[82:97], v[192:195], v[154:157], v[82:97]
	v_add_u32_e32 v99, 0x18e60, v181
	ds_read_b128 v[196:199], v99
	v_exp_f32_e32 v164, v115
	v_exp_f32_e32 v118, v118
	v_exp_f32_e32 v158, v108
	v_exp_f32_e32 v167, v109
	v_exp_f32_e32 v161, v110
	s_waitcnt lgkmcnt(3)
	v_mfma_f32_32x32x16_bf16 v[130:145], v[126:129], v[150:153], v[130:145]
	v_exp_f32_e32 v126, v113
	v_exp_f32_e32 v129, v107
	v_exp_f32_e32 v115, v123
	v_exp_f32_e32 v123, v125
	v_exp_f32_e32 v170, v104
	v_exp_f32_e32 v171, v105
	v_exp_f32_e32 v172, v106
	s_waitcnt lgkmcnt(2)
	v_mfma_f32_32x32x16_bf16 v[82:97], v[174:177], v[150:153], v[82:97]
	v_exp_f32_e32 v127, v111
	v_exp_f32_e32 v128, v112
	s_waitcnt lgkmcnt(1)
	v_mfma_f32_32x32x16_bf16 v[130:145], v[100:103], v[146:149], v[130:145]
	s_waitcnt lgkmcnt(0)
	v_mfma_f32_32x32x16_bf16 v[82:97], v[196:199], v[146:149], v[82:97]
	s_nop 9
	v_exp_f32_e32 v99, v130
	v_exp_f32_e32 v100, v131
	v_exp_f32_e32 v113, v132
	v_exp_f32_e32 v101, v133
	v_exp_f32_e32 v102, v134
	v_exp_f32_e32 v103, v135
	v_add_u32_e32 v131, 0x1ba00, v185
	v_exp_f32_e32 v130, v82
	v_add_u32_e32 v82, 0x1b000, v185
	ds_read_b64_tr_b16 v[132:133], v82
	ds_read_b64_tr_b16 v[134:135], v131
	v_add_u32_e32 v82, 0x1b040, v185
	v_exp_f32_e32 v107, v140
	v_exp_f32_e32 v108, v141
	v_exp_f32_e32 v109, v142
	v_exp_f32_e32 v110, v143
	v_add_u32_e32 v131, 0x1ba40, v185
	ds_read_b64_tr_b16 v[140:141], v82
	ds_read_b64_tr_b16 v[142:143], v131
	v_exp_f32_e32 v156, v84
	v_add_u32_e32 v82, 0x1b080, v185
	v_add_u32_e32 v84, 0x1ba80, v185
	v_exp_f32_e32 v131, v83
	v_exp_f32_e32 v157, v85
	ds_read_b64_tr_b16 v[82:83], v82
	ds_read_b64_tr_b16 v[84:85], v84
	v_exp_f32_e32 v104, v136
	v_exp_f32_e32 v105, v137
	v_exp_f32_e32 v106, v138
	v_exp_f32_e32 v125, v139
	v_cvt_pk_bf16_f32 v136, v163, v164
	v_cvt_pk_bf16_f32 v137, v165, v162
	v_cvt_pk_bf16_f32 v138, v118, v116
	v_cvt_pk_bf16_f32 v139, v117, v98
	v_exp_f32_e32 v174, v86
	v_add_u32_e32 v86, 0x1b0c0, v185
	s_waitcnt lgkmcnt(4)
	v_mfma_f32_32x32x16_bf16 v[50:65], v[132:135], v[136:139], v[50:65]
	v_exp_f32_e32 v175, v87
	v_add_u32_e32 v87, 0x1bac0, v185
	ds_read_b64_tr_b16 v[132:133], v86
	ds_read_b64_tr_b16 v[134:135], v87
	v_exp_f32_e32 v176, v88
	v_exp_f32_e32 v177, v89
	v_cvt_pk_bf16_f32 v86, v114, v115
	v_cvt_pk_bf16_f32 v87, v122, v123
	s_waitcnt lgkmcnt(2)
	v_mfma_f32_32x32x16_bf16 v[34:49], v[82:85], v[136:139], v[34:49]
	v_add_u32_e32 v82, 0x1c400, v185
	v_add_u32_e32 v84, 0x1ce00, v185
	ds_read_b64_tr_b16 v[82:83], v82
	ds_read_b64_tr_b16 v[84:85], v84
	v_cvt_pk_bf16_f32 v88, v119, v120
	v_cvt_pk_bf16_f32 v89, v121, v124
	v_exp_f32_e32 v192, v90
	v_add_u32_e32 v90, 0x1c440, v185
	v_mfma_f32_32x32x16_bf16 v[66:81], v[140:143], v[136:139], v[66:81]
	v_exp_f32_e32 v193, v91
	v_exp_f32_e32 v91, v93
	v_exp_f32_e32 v93, v95
	v_add_u32_e32 v95, 0x1c4c0, v185
	v_exp_f32_e32 v111, v144
	v_add_u32_e32 v144, 0x1ec40, v185
	v_exp_f32_e32 v112, v145
	s_waitcnt lgkmcnt(2)
	v_mfma_f32_32x32x16_bf16 v[18:33], v[132:135], v[136:139], v[18:33]
	v_add_u32_e32 v134, 0x1ce40, v185
	ds_read_b64_tr_b16 v[132:133], v90
	ds_read_b64_tr_b16 v[134:135], v134
	v_exp_f32_e32 v90, v92
	v_exp_f32_e32 v92, v94
	v_exp_f32_e32 v94, v96
	v_add_u32_e32 v96, 0x1cec0, v185
	v_cvt_pk_bf16_f32 v136, v166, v168
	s_waitcnt lgkmcnt(2)
	v_mfma_f32_32x32x16_bf16 v[50:65], v[82:85], v[86:89], v[50:65]
	v_add_u32_e32 v82, 0x1c480, v185
	v_add_u32_e32 v84, 0x1ce80, v185
	ds_read_b64_tr_b16 v[82:83], v82
	ds_read_b64_tr_b16 v[84:85], v84
	v_cvt_pk_bf16_f32 v137, v169, v173
	v_cvt_pk_bf16_f32 v138, v160, v159
	v_cvt_pk_bf16_f32 v139, v170, v171
	s_waitcnt lgkmcnt(0)
	v_mfma_f32_32x32x16_bf16 v[34:49], v[82:85], v[86:89], v[34:49]
	v_add_u32_e32 v82, 0x1d800, v185
	v_add_u32_e32 v84, 0x1e200, v185
	v_mfma_f32_32x32x16_bf16 v[66:81], v[132:135], v[86:89], v[66:81]
	ds_read_b64_tr_b16 v[132:133], v95
	ds_read_b64_tr_b16 v[134:135], v96
	ds_read_b64_tr_b16 v[82:83], v82
	ds_read_b64_tr_b16 v[84:85], v84
	v_add_u32_e32 v96, 0x1d880, v185
	v_exp_f32_e32 v95, v97
	v_add_u32_e32 v97, 0x1d8c0, v185
	s_waitcnt lgkmcnt(2)
	v_mfma_f32_32x32x16_bf16 v[18:33], v[132:135], v[86:89], v[18:33]
	v_add_u32_e32 v86, 0x1d840, v185
	v_add_u32_e32 v88, 0x1e240, v185
	v_add_u32_e32 v134, 0x1e2c0, v185
	ds_read_b64_tr_b16 v[86:87], v86
	ds_read_b64_tr_b16 v[88:89], v88
	s_waitcnt lgkmcnt(2)
	v_mfma_f32_32x32x16_bf16 v[50:65], v[82:85], v[136:139], v[50:65]
	v_add_u32_e32 v84, 0x1e280, v185
	ds_read_b64_tr_b16 v[82:83], v96
	ds_read_b64_tr_b16 v[84:85], v84
	ds_read_b64_tr_b16 v[132:133], v97
	ds_read_b64_tr_b16 v[134:135], v134
	v_add_u32_e32 v96, 0x1ec00, v185
	v_add_u32_e32 v97, 0x1f600, v185
	ds_read_b64_tr_b16 v[140:141], v96
	ds_read_b64_tr_b16 v[142:143], v97
	ds_read_b64_tr_b16 v[144:145], v144
	v_add_f32_e32 v96, 0, v166
	v_add_f32_e32 v96, v168, v96
	v_add_f32_e32 v96, v169, v96
	v_add_f32_e32 v96, v173, v96
	s_waitcnt lgkmcnt(5)
	v_mfma_f32_32x32x16_bf16 v[34:49], v[82:85], v[136:139], v[34:49]
	v_add_u32_e32 v82, 0x1f640, v185
	v_add_f32_e32 v97, v160, v96
	ds_read_b64_tr_b16 v[146:147], v82
	v_add_u32_e32 v82, 0x1ec80, v185
	v_add_f32_e32 v97, v159, v97
	ds_read_b64_tr_b16 v[148:149], v82
	v_add_u32_e32 v82, 0x1f680, v185
	v_add_f32_e32 v97, v170, v97
	ds_read_b64_tr_b16 v[150:151], v82
	v_add_u32_e32 v82, 0x1ecc0, v185
	v_add_f32_e32 v97, v171, v97
	v_mfma_f32_32x32x16_bf16 v[66:81], v[86:89], v[136:139], v[66:81]
	v_cvt_pk_bf16_f32 v86, v172, v129
	v_cvt_pk_bf16_f32 v87, v158, v167
	v_cvt_pk_bf16_f32 v88, v161, v127
	v_cvt_pk_bf16_f32 v89, v128, v126
	ds_read_b64_tr_b16 v[152:153], v82
	v_add_u32_e32 v82, 0x1f6c0, v185
	v_add_f32_e32 v97, v172, v97
	ds_read_b64_tr_b16 v[154:155], v82
	s_waitcnt lgkmcnt(6)
	v_mfma_f32_32x32x16_bf16 v[50:65], v[140:143], v[86:89], v[50:65]
	v_add_u32_e32 v140, 0x20000, v185
	v_add_u32_e32 v142, 0x20a00, v185
	v_add_f32_e32 v97, v129, v97
	ds_read_b64_tr_b16 v[140:141], v140
	ds_read_b64_tr_b16 v[142:143], v142
	v_add_f32_e32 v97, v158, v97
	v_add_f32_e32 v97, v167, v97
	v_mfma_f32_32x32x16_bf16 v[18:33], v[132:135], v[136:139], v[18:33]
	v_add_f32_e32 v97, v161, v97
	v_add_f32_e32 v97, v127, v97
	v_add_f32_e32 v97, v128, v97
	v_add_f32_e32 v97, v126, v97
	v_cvt_pk_bf16_f32 v136, v130, v131
	v_add_u32_e32 v129, 0x200c0, v185
	v_add_f32_e32 v97, v130, v97
	v_add_f32_e32 v130, 0, v163
	s_waitcnt lgkmcnt(4)
	v_mfma_f32_32x32x16_bf16 v[34:49], v[148:151], v[86:89], v[34:49]
	ds_read_b64_tr_b16 v[148:149], v129
	v_add_u32_e32 v129, 0x20ac0, v185
	v_add_u32_e32 v126, 0x21400, v185
	v_add_u32_e32 v128, 0x21e00, v185
	v_add_f32_e32 v130, v164, v130
	v_cvt_pk_bf16_f32 v82, v99, v100
	v_cvt_pk_bf16_f32 v83, v113, v101
	v_cvt_pk_bf16_f32 v84, v102, v103
	v_cvt_pk_bf16_f32 v85, v104, v105
	v_mfma_f32_32x32x16_bf16 v[66:81], v[144:147], v[86:89], v[66:81]
	ds_read_b64_tr_b16 v[150:151], v129
	ds_read_b64_tr_b16 v[126:127], v126
	ds_read_b64_tr_b16 v[128:129], v128
	v_add_f32_e32 v130, v165, v130
	v_add_f32_e32 v130, v162, v130
	v_add_f32_e32 v118, v118, v130
	v_add_f32_e32 v116, v116, v118
	s_waitcnt lgkmcnt(6)
	v_mfma_f32_32x32x16_bf16 v[18:33], v[152:155], v[86:89], v[18:33]
	v_add_u32_e32 v86, 0x20080, v185
	v_add_u32_e32 v88, 0x20a80, v185
	ds_read_b64_tr_b16 v[86:87], v86
	ds_read_b64_tr_b16 v[88:89], v88
	v_add_u32_e32 v144, 0x20040, v185
	v_add_u32_e32 v146, 0x20a40, v185
	v_add_f32_e32 v116, v117, v116
	s_waitcnt lgkmcnt(6)
	v_mfma_f32_32x32x16_bf16 v[50:65], v[140:143], v[82:85], v[50:65]
	ds_read_b64_tr_b16 v[144:145], v144
	ds_read_b64_tr_b16 v[146:147], v146
	v_add_f32_e32 v98, v98, v116
	v_add_f32_e32 v98, v114, v98
	v_add_f32_e32 v98, v115, v98
	v_cvt_pk_bf16_f32 v132, v106, v125
	v_cvt_pk_bf16_f32 v133, v107, v108
	v_cvt_pk_bf16_f32 v134, v109, v110
	v_cvt_pk_bf16_f32 v135, v111, v112
	v_add_f32_e32 v98, v122, v98
	v_add_f32_e32 v98, v123, v98
	s_waitcnt lgkmcnt(4)
	v_mfma_f32_32x32x16_bf16 v[50:65], v[126:129], v[132:135], v[50:65]
	v_add_f32_e32 v98, v119, v98
	v_add_f32_e32 v98, v120, v98
	v_add_f32_e32 v97, v131, v97
	v_add_f32_e32 v98, v121, v98
	v_add_u32_e32 v140, 0x21440, v185
	v_add_u32_e32 v142, 0x21e40, v185
	v_add_f32_e32 v97, v156, v97
	s_waitcnt lgkmcnt(2)
	v_mfma_f32_32x32x16_bf16 v[34:49], v[86:89], v[82:85], v[34:49]
	v_add_f32_e32 v98, v124, v98
	v_cvt_pk_bf16_f32 v137, v156, v157
	ds_read_b64_tr_b16 v[140:141], v140
	ds_read_b64_tr_b16 v[142:143], v142
	v_add_f32_e32 v97, v157, v97
	v_add_f32_e32 v98, v99, v98
	v_add_f32_e32 v98, v100, v98
	s_waitcnt lgkmcnt(2)
	v_mfma_f32_32x32x16_bf16 v[66:81], v[144:147], v[82:85], v[66:81]
	ds_read_b64_tr_b16 v[144:145], v238
	ds_read_b64_tr_b16 v[146:147], v239
	ds_read_b64_tr_b16 v[152:153], v240
	ds_read_b64_tr_b16 v[154:155], v241
	ds_read_b64_tr_b16 v[86:87], v242
	ds_read_b64_tr_b16 v[88:89], v243
	ds_read_b64_tr_b16 v[156:157], v244
	ds_read_b64_tr_b16 v[158:159], v245
	v_cvt_pk_bf16_f32 v138, v174, v175
	v_cvt_pk_bf16_f32 v139, v176, v177
	v_add_f32_e32 v98, v113, v98
	v_add_f32_e32 v97, v174, v97
	v_add_f32_e32 v97, v175, v97
	s_waitcnt lgkmcnt(2)
	v_mfma_f32_32x32x16_bf16 v[50:65], v[86:89], v[136:139], v[50:65]
	v_add_f32_e32 v86, v101, v98
	v_add_f32_e32 v86, v102, v86
	v_add_f32_e32 v86, v103, v86
	v_add_f32_e32 v97, v176, v97
	v_add_f32_e32 v86, v104, v86
	v_add_f32_e32 v97, v177, v97
	v_add_f32_e32 v86, v105, v86
	v_mfma_f32_32x32x16_bf16 v[34:49], v[144:147], v[132:135], v[34:49]
	v_add_f32_e32 v97, v192, v97
	v_add_f32_e32 v86, v106, v86
	v_add_f32_e32 v97, v193, v97
	v_add_f32_e32 v86, v125, v86
	v_add_f32_e32 v97, v90, v97
	v_add_f32_e32 v86, v107, v86
	v_add_f32_e32 v97, v91, v97
	v_mfma_f32_32x32x16_bf16 v[18:33], v[148:151], v[82:85], v[18:33]
	ds_read_b64_tr_b16 v[82:83], v246
	ds_read_b64_tr_b16 v[84:85], v247
	ds_read_b64_tr_b16 v[148:149], v248
	ds_read_b64_tr_b16 v[150:151], v249
	v_add_f32_e32 v86, v108, v86
	v_add_f32_e32 v97, v92, v97
	v_add_f32_e32 v86, v109, v86
	ds_read_b64_tr_b16 v[126:127], v250
	ds_read_b64_tr_b16 v[128:129], v251
	ds_read_b64_tr_b16 v[164:165], v252
	ds_read_b64_tr_b16 v[166:167], v253
	v_add_f32_e32 v97, v93, v97
	v_add_f32_e32 v86, v110, v86
	s_waitcnt lgkmcnt(6)
	v_mfma_f32_32x32x16_bf16 v[34:49], v[82:85], v[136:139], v[34:49]
	v_mov_b32_e32 v83, v179
	v_add_f32_e32 v97, v94, v97
	v_add_f32_e32 v86, v111, v86
	v_add_f32_e32 v97, v95, v97
	v_add_f32_e32 v86, v112, v86
	v_add_f32_e32 v86, v86, v97
	v_add_f32_e32 v82, v191, v86
	v_mfma_f32_32x32x16_bf16 v[66:81], v[140:143], v[132:135], v[66:81]
	ds_read_b64_tr_b16 v[140:141], v254
	ds_read_b64_tr_b16 v[142:143], v187
	ds_read_b64_tr_b16 v[160:161], v222
	ds_read_b64_tr_b16 v[162:163], v223
	s_waitcnt lgkmcnt(0)
	s_barrier
	v_cvt_pk_bf16_f32 v96, v192, v193
	v_mbcnt_lo_u32_b32 v83, -1, v83
	v_mfma_f32_32x32x16_bf16 v[18:33], v[152:155], v[132:135], v[18:33]
	v_mbcnt_hi_u32_b32 v87, -1, v83
	v_lshlrev_b32_e32 v83, 2, v87
	v_xor_b32_e32 v85, 0x80, v83
	ds_bpermute_b32 v83, v85, v82
	v_cvt_pk_bf16_f32 v97, v90, v91
	v_cvt_pk_bf16_f32 v98, v92, v93
	v_cvt_pk_bf16_f32 v99, v94, v95
	v_mfma_f32_32x32x16_bf16 v[66:81], v[156:159], v[136:139], v[66:81]
	s_waitcnt lgkmcnt(0)
	v_add_f32_e32 v82, v82, v83
	v_div_scale_f32 v83, s[44:45], v82, v82, 1.0
	v_rcp_f32_e32 v84, v83
	s_nop 0
	v_fma_f32 v86, -v83, v84, 1.0
	v_mfma_f32_32x32x16_bf16 v[18:33], v[148:151], v[136:139], v[18:33]
	v_fmac_f32_e32 v84, v86, v84
	v_div_scale_f32 v86, vcc, 1.0, v82, 1.0
	v_mul_f32_e32 v88, v86, v84
	v_fma_f32 v89, -v83, v88, v86
	v_fmac_f32_e32 v88, v89, v84
	v_fma_f32 v83, -v83, v88, v86
	v_mfma_f32_32x32x16_bf16 v[50:65], v[126:129], v[96:99], v[50:65]
	v_div_fmas_f32 v83, v83, v84, v88
	v_and_b32_e32 v86, 31, v87
	v_ashrrev_i32_e32 v87, 5, v87
	v_div_fixup_f32 v83, v83, v82, 1.0
	v_lshlrev_b32_e32 v82, 9, v87
	v_lshlrev_b32_e32 v88, 2, v86
	v_mul_f32_e32 v84, v224, v83
	v_mfma_f32_32x32x16_bf16 v[66:81], v[164:167], v[96:99], v[66:81]
	s_and_b64 vcc, exec, s[6:7]
	v_add3_u32 v82, s28, v82, v88
	v_mfma_f32_32x32x16_bf16 v[34:49], v[140:143], v[96:99], v[34:49]
	v_mfma_f32_32x32x16_bf16 v[18:33], v[160:163], v[96:99], v[18:33]
	s_cbranch_vccnz .LBB0_658
	v_mul_f32_e32 v88, v50, v84
	v_mul_f32_e32 v89, v51, v84
	ds_write2_b32 v82, v88, v89 offset1:32
	v_mul_f32_e32 v88, v52, v84
	v_mul_f32_e32 v89, v53, v84
	ds_write2_b32 v82, v88, v89 offset0:64 offset1:96
	v_mul_f32_e32 v88, v54, v84
	v_mul_f32_e32 v89, v55, v84
	v_add_u32_e32 v90, 0x400, v82
	ds_write2_b32 v90, v88, v89 offset1:32
	v_mul_f32_e32 v88, v56, v84
	v_mul_f32_e32 v89, v57, v84
	ds_write2_b32 v90, v88, v89 offset0:64 offset1:96
	v_mul_f32_e32 v88, v58, v84
	v_mul_f32_e32 v89, v59, v84
	v_add_u32_e32 v90, 0x800, v82
	ds_write2_b32 v90, v88, v89 offset1:32
	v_mul_f32_e32 v88, v60, v84
	v_mul_f32_e32 v89, v61, v84
	ds_write2_b32 v90, v88, v89 offset0:64 offset1:96
	v_mul_f32_e32 v88, v62, v84
	v_mul_f32_e32 v89, v63, v84
	v_add_u32_e32 v90, 0xc00, v82
	ds_write2_b32 v90, v88, v89 offset1:32
	v_mul_f32_e32 v88, v64, v84
	v_mul_f32_e32 v89, v65, v84
	ds_write2_b32 v90, v88, v89 offset0:64 offset1:96
	v_mul_f32_e32 v88, v66, v84
	v_mul_f32_e32 v89, v67, v84
	v_add_u32_e32 v90, 0x1000, v82
	ds_write2_b32 v90, v88, v89 offset1:32
	v_mul_f32_e32 v88, v68, v84
	v_mul_f32_e32 v89, v69, v84
	ds_write2_b32 v90, v88, v89 offset0:64 offset1:96
	v_mul_f32_e32 v88, v70, v84
	v_mul_f32_e32 v89, v71, v84
	v_add_u32_e32 v90, 0x1400, v82
	ds_write2_b32 v90, v88, v89 offset1:32
	v_mul_f32_e32 v88, v72, v84
	v_mul_f32_e32 v89, v73, v84
	ds_write2_b32 v90, v88, v89 offset0:64 offset1:96
	v_mul_f32_e32 v88, v74, v84
	v_mul_f32_e32 v89, v75, v84
	v_add_u32_e32 v90, 0x1800, v82
	ds_write2_b32 v90, v88, v89 offset1:32
	v_mul_f32_e32 v88, v76, v84
	v_mul_f32_e32 v89, v77, v84
	ds_write2_b32 v90, v88, v89 offset0:64 offset1:96
	v_mul_f32_e32 v88, v78, v84
	v_mul_f32_e32 v89, v79, v84
	v_add_u32_e32 v90, 0x1c00, v82
	ds_write2_b32 v90, v88, v89 offset1:32
	v_mul_f32_e32 v88, v80, v84
	v_mul_f32_e32 v89, v81, v84
	ds_write2_b32 v90, v88, v89 offset0:64 offset1:96
	v_mul_f32_e32 v88, v34, v84
	v_mul_f32_e32 v89, v35, v84
	v_add_u32_e32 v90, 0x2000, v82
	ds_write2_b32 v90, v88, v89 offset1:32
	v_mul_f32_e32 v88, v36, v84
	v_mul_f32_e32 v89, v37, v84
	ds_write2_b32 v90, v88, v89 offset0:64 offset1:96
	v_mul_f32_e32 v88, v38, v84
	v_mul_f32_e32 v89, v39, v84
	v_add_u32_e32 v90, 0x2400, v82
	ds_write2_b32 v90, v88, v89 offset1:32
	v_mul_f32_e32 v88, v40, v84
	v_mul_f32_e32 v89, v41, v84
	ds_write2_b32 v90, v88, v89 offset0:64 offset1:96
	v_mul_f32_e32 v88, v42, v84
	v_mul_f32_e32 v89, v43, v84
	v_add_u32_e32 v90, 0x2800, v82
	ds_write2_b32 v90, v88, v89 offset1:32
	v_mul_f32_e32 v88, v44, v84
	v_mul_f32_e32 v89, v45, v84
	ds_write2_b32 v90, v88, v89 offset0:64 offset1:96
	v_mul_f32_e32 v88, v46, v84
	v_mul_f32_e32 v89, v47, v84
	v_add_u32_e32 v90, 0x2c00, v82
	ds_write2_b32 v90, v88, v89 offset1:32
	v_mul_f32_e32 v88, v48, v84
	v_mul_f32_e32 v89, v49, v84
	ds_write2_b32 v90, v88, v89 offset0:64 offset1:96
	v_mul_f32_e32 v88, v18, v84
	v_mul_f32_e32 v89, v19, v84
	v_add_u32_e32 v90, 0x3000, v82
	ds_write2_b32 v90, v88, v89 offset1:32
	v_mul_f32_e32 v88, v20, v84
	v_mul_f32_e32 v89, v21, v84
	ds_write2_b32 v90, v88, v89 offset0:64 offset1:96
	v_mul_f32_e32 v88, v22, v84
	v_mul_f32_e32 v89, v23, v84
	v_add_u32_e32 v90, 0x3400, v82
	ds_write2_b32 v90, v88, v89 offset1:32
	v_mul_f32_e32 v88, v24, v84
	v_mul_f32_e32 v89, v25, v84
	ds_write2_b32 v90, v88, v89 offset0:64 offset1:96
	v_mul_f32_e32 v88, v26, v84
	v_mul_f32_e32 v89, v27, v84
	v_add_u32_e32 v90, 0x3800, v82
	ds_write2_b32 v90, v88, v89 offset1:32
	v_mul_f32_e32 v88, v28, v84
	v_mul_f32_e32 v89, v29, v84
	ds_write2_b32 v90, v88, v89 offset0:64 offset1:96
	v_mul_f32_e32 v88, v30, v84
	v_mul_f32_e32 v89, v31, v84
	v_add_u32_e32 v90, 0x3c00, v82
	ds_write2_b32 v90, v88, v89 offset1:32
	v_mul_f32_e32 v88, v32, v84
	v_mul_f32_e32 v89, v33, v84
	ds_write2_b32 v90, v88, v89 offset0:64 offset1:96
